# hand-scheduled SwiGLU epilogue for the GU GEMM (packed f32 math, no hazard nops or register moves, same operation order); scalar phase header
# speedup vs baseline: 1.0174x; 1.0174x over previous
; __device__ __forceinline__ unsigned cvt_pk_bf16(float lo, float hi) { unsigned r; asm volatile("v_cvt_pk_bf16_f32 %0, %1, %2" : "=v"(r) : "v"(lo), "v"(hi)); return r; }
; __device__ __forceinline__ float siluf_(float x) { return x * sigmoidf_(x); }
; __device__ __forceinline__ void load_rstd(float (&rsv)[2][4], const ssq_t* ssq, int row0) {
;     ssq_t t[2][4];
; #pragma unroll
;     for (int ai = 0; ai < 2; ++ai)
; #pragma unroll
;         for (int m = 0; m < 4; ++m) t[ai][m] = ssq[row0 + ai * HALF + m * 16];
; #pragma unroll
;     for (int ai = 0; ai < 2; ++ai)
; #pragma unroll
;         for (int m = 0; m < 4; ++m) rsv[ai][m] = __builtin_amdgcn_rsqf((float)t[ai][m] * (SSQ_INV / 1024.0f) + 1e-6f);
; }
;     __device__ __forceinline__ void operator()(const f32x4 (&acc)[2][2][4][2], const Unit& u, int wr, int wc, int fr, int fq) const {
;         const int row0 = u.pm * BM + wr * 64 + fr, col0 = u.pn * HALF + wc * 32 + 8 * fq;
;         float rsv[2][4]; load_rstd(rsv, ssq, row0);
; #pragma unroll
;         for (int ai = 0; ai < 2; ++ai)
; #pragma unroll
;             for (int m = 0; m < 4; ++m) { const int row = row0 + ai * HALF + m * 16; bf16_t* rowp = O + (size_t)row * ldc + col0; const float rs = rsv[ai][m];
;                 f32x4 v0, v1;
; #pragma unroll
;                 for (int j = 0; j < 4; ++j) { v0[j] = siluf_(acc[ai][0][m][0][j] * rs) * (acc[ai][1][m][0][j] * rs); v1[j] = siluf_(acc[ai][0][m][1][j] * rs) * (acc[ai][1][m][1][j] * rs); }
;                 u32x4 w; w.x = cvt_pk_bf16(v0[0], v0[1]); w.y = cvt_pk_bf16(v0[2], v0[3]); w.z = cvt_pk_bf16(v1[0], v1[1]); w.w = cvt_pk_bf16(v1[2], v1[3]);
;                 *(u32x4*)rowp = w; }
.LBB0_311:
	v_lshrrev_b32_e32 v150, 8, v170
	v_and_b32_e32 v152, 15, v170
	v_lshl_add_u32 v150, v150, 6, v152
	s_lshl_b32 s10, s64, 8
	v_add_u32_e32 v150, s10, v150
	v_lshlrev_b32_e32 v142, 3, v150
	v_mov_b32_e32 v143, 0
	v_lshl_add_u64 v[142:143], v[142:143], 0, s[26:27]
	global_load_dwordx2 v[144:145], v[142:143], off
	global_load_dwordx2 v[146:147], v[142:143], off offset:128
	global_load_dwordx2 v[148:149], v[142:143], off offset:256
	global_load_dwordx2 v[154:155], v[142:143], off offset:384
	global_load_dwordx2 v[156:157], v[142:143], off offset:1024
	global_load_dwordx2 v[158:159], v[142:143], off offset:1152
	global_load_dwordx2 v[162:163], v[142:143], off offset:1280
	global_load_dwordx2 v[164:165], v[142:143], off offset:1408
	v_bfe_u32 v152, v170, 6, 2
	v_bfe_u32 v160, v170, 4, 2
	v_lshlrev_b32_e32 v152, 5, v152
	v_lshl_or_b32 v152, v160, 3, v152
	s_lshl_b32 s10, s63, 7
	v_add_u32_e32 v152, s10, v152
	v_mul_lo_u32 v150, v150, s28
	v_add_lshl_u32 v150, v150, v152, 1
	v_mov_b32_e32 v166, 0xbfb8aa3b
	v_mov_b32_e32 v167, 0xbfb8aa3b
	s_lshl_b32 s98, s28, 5
	s_mov_b32 s99, 0
	s_mul_i32 s100, s28, 0xa0
	s_mov_b32 s101, 0
	s_waitcnt vmcnt(0)
	v_mov_b32_e32 v142, v150
	v_mov_b32_e32 v143, 0
	v_lshl_add_u64 v[142:143], v[142:143], 0, s[30:31]
	v_ffbh_u32_e32 v150, v145
	v_min_u32_e32 v150, 32, v150
	v_lshlrev_b64 v[144:145], v150, v[144:145]
	v_min_u32_e32 v144, 1, v144
	v_or_b32_e32 v144, v145, v144
	v_cvt_f32_u32_e32 v144, v144
	v_sub_u32_e32 v150, 32, v150
	v_ldexp_f32 v144, v144, v150
	v_fmamk_f32 v144, v144, 0x30800000, v223
	v_rsq_f32_e32 v144, v144
	v_ffbh_u32_e32 v150, v147
	v_min_u32_e32 v150, 32, v150
	v_lshlrev_b64 v[146:147], v150, v[146:147]
	v_min_u32_e32 v146, 1, v146
	v_or_b32_e32 v146, v147, v146
	v_cvt_f32_u32_e32 v146, v146
	v_sub_u32_e32 v150, 32, v150
	v_ldexp_f32 v146, v146, v150
	v_fmamk_f32 v146, v146, 0x30800000, v223
	v_rsq_f32_e32 v146, v146
	v_ffbh_u32_e32 v150, v149
	v_min_u32_e32 v150, 32, v150
	v_lshlrev_b64 v[148:149], v150, v[148:149]
	v_min_u32_e32 v148, 1, v148
	v_or_b32_e32 v148, v149, v148
	v_cvt_f32_u32_e32 v148, v148
	v_sub_u32_e32 v150, 32, v150
	v_ldexp_f32 v148, v148, v150
	v_fmamk_f32 v148, v148, 0x30800000, v223
	v_rsq_f32_e32 v148, v148
	v_ffbh_u32_e32 v150, v155
	v_min_u32_e32 v150, 32, v150
	v_lshlrev_b64 v[154:155], v150, v[154:155]
	v_min_u32_e32 v154, 1, v154
	v_or_b32_e32 v154, v155, v154
	v_cvt_f32_u32_e32 v154, v154
	v_sub_u32_e32 v150, 32, v150
	v_ldexp_f32 v154, v154, v150
	v_fmamk_f32 v154, v154, 0x30800000, v223
	v_rsq_f32_e32 v154, v154
	v_ffbh_u32_e32 v150, v157
	v_min_u32_e32 v150, 32, v150
	v_lshlrev_b64 v[156:157], v150, v[156:157]
	v_min_u32_e32 v156, 1, v156
	v_or_b32_e32 v156, v157, v156
	v_cvt_f32_u32_e32 v156, v156
	v_sub_u32_e32 v150, 32, v150
	v_ldexp_f32 v156, v156, v150
	v_fmamk_f32 v156, v156, 0x30800000, v223
	v_rsq_f32_e32 v156, v156
	v_ffbh_u32_e32 v150, v159
	v_min_u32_e32 v150, 32, v150
	v_lshlrev_b64 v[158:159], v150, v[158:159]
	v_min_u32_e32 v158, 1, v158
	v_or_b32_e32 v158, v159, v158
	v_cvt_f32_u32_e32 v158, v158
	v_sub_u32_e32 v150, 32, v150
	v_ldexp_f32 v158, v158, v150
	v_fmamk_f32 v158, v158, 0x30800000, v223
	v_rsq_f32_e32 v158, v158
	v_ffbh_u32_e32 v150, v163
	v_min_u32_e32 v150, 32, v150
	v_lshlrev_b64 v[162:163], v150, v[162:163]
	v_min_u32_e32 v162, 1, v162
	v_or_b32_e32 v162, v163, v162
	v_cvt_f32_u32_e32 v162, v162
	v_sub_u32_e32 v150, 32, v150
	v_ldexp_f32 v162, v162, v150
	v_fmamk_f32 v162, v162, 0x30800000, v223
	v_rsq_f32_e32 v162, v162
	v_ffbh_u32_e32 v150, v165
	v_min_u32_e32 v150, 32, v150
	v_lshlrev_b64 v[164:165], v150, v[164:165]
	v_min_u32_e32 v164, 1, v164
	v_or_b32_e32 v164, v165, v164
	v_cvt_f32_u32_e32 v164, v164
	v_sub_u32_e32 v150, 32, v150
	v_ldexp_f32 v164, v164, v150
	v_fmamk_f32 v164, v164, 0x30800000, v223
	v_rsq_f32_e32 v164, v164
	v_mov_b32_e32 v145, v146
	v_mov_b32_e32 v146, v148
	v_mov_b32_e32 v147, v154
	v_mov_b32_e32 v148, v156
	v_mov_b32_e32 v149, v158
	v_mov_b32_e32 v154, v162
	v_mov_b32_e32 v155, v164
	v_pk_mul_f32 v[120:121], v[120:121], v[144:145] op_sel_hi:[1,0]
	v_pk_mul_f32 v[122:123], v[122:123], v[144:145] op_sel_hi:[1,0]
	v_pk_mul_f32 v[112:113], v[112:113], v[144:145] op_sel_hi:[1,0]
	v_pk_mul_f32 v[114:115], v[114:115], v[144:145] op_sel_hi:[1,0]
	v_pk_mul_f32 v[124:125], v[124:125], v[144:145] op_sel_hi:[1,0]
	v_pk_mul_f32 v[126:127], v[126:127], v[144:145] op_sel_hi:[1,0]
	v_pk_mul_f32 v[116:117], v[116:117], v[144:145] op_sel_hi:[1,0]
	v_pk_mul_f32 v[118:119], v[118:119], v[144:145] op_sel_hi:[1,0]
	v_pk_mul_f32 v[156:157], v[120:121], v[166:167]
	v_pk_mul_f32 v[158:159], v[122:123], v[166:167]
	v_pk_mul_f32 v[162:163], v[112:113], v[166:167]
	v_pk_mul_f32 v[164:165], v[114:115], v[166:167]
	v_exp_f32_e32 v156, v156
	v_exp_f32_e32 v157, v157
	v_exp_f32_e32 v158, v158
	v_exp_f32_e32 v159, v159
	v_exp_f32_e32 v162, v162
	v_exp_f32_e32 v163, v163
	v_exp_f32_e32 v164, v164
	v_exp_f32_e32 v165, v165
	v_add_f32_e32 v156, 1.0, v156
	v_add_f32_e32 v157, 1.0, v157
	v_add_f32_e32 v158, 1.0, v158
	v_add_f32_e32 v159, 1.0, v159
	v_add_f32_e32 v162, 1.0, v162
	v_add_f32_e32 v163, 1.0, v163
	v_add_f32_e32 v164, 1.0, v164
	v_add_f32_e32 v165, 1.0, v165
	v_rcp_f32_e32 v156, v156
	v_rcp_f32_e32 v157, v157
	v_rcp_f32_e32 v158, v158
	v_rcp_f32_e32 v159, v159
	v_rcp_f32_e32 v162, v162
	v_rcp_f32_e32 v163, v163
	v_rcp_f32_e32 v164, v164
	v_rcp_f32_e32 v165, v165
	v_pk_mul_f32 v[120:121], v[120:121], v[156:157]
	v_pk_mul_f32 v[122:123], v[122:123], v[158:159]
	v_pk_mul_f32 v[112:113], v[112:113], v[162:163]
	v_pk_mul_f32 v[114:115], v[114:115], v[164:165]
	v_pk_mul_f32 v[120:121], v[120:121], v[124:125]
; __device__ __forceinline__ unsigned cvt_pk_bf16(float lo, float hi) { unsigned r; asm volatile("v_cvt_pk_bf16_f32 %0, %1, %2" : "=v"(r) : "v"(lo), "v"(hi)); return r; }
; __device__ __forceinline__ float siluf_(float x) { return x * sigmoidf_(x); }
;     __device__ __forceinline__ void operator()(const f32x4 (&acc)[2][2][4][2], const Unit& u, int wr, int wc, int fr, int fq) const {
;     ...
;         for (int ai = 0; ai < 2; ++ai)
; #pragma unroll
;             for (int m = 0; m < 4; ++m) { const int row = row0 + ai * HALF + m * 16; bf16_t* rowp = O + (size_t)row * ldc + col0; const float rs = rsv[ai][m];
;                 f32x4 v0, v1;
; #pragma unroll
;                 for (int j = 0; j < 4; ++j) { v0[j] = siluf_(acc[ai][0][m][0][j] * rs) * (acc[ai][1][m][0][j] * rs); v1[j] = siluf_(acc[ai][0][m][1][j] * rs) * (acc[ai][1][m][1][j] * rs); }
;                 u32x4 w; w.x = cvt_pk_bf16(v0[0], v0[1]); w.y = cvt_pk_bf16(v0[2], v0[3]); w.z = cvt_pk_bf16(v1[0], v1[1]); w.w = cvt_pk_bf16(v1[2], v1[3]);
;                 *(u32x4*)rowp = w; }
	v_pk_mul_f32 v[122:123], v[122:123], v[126:127]
	v_pk_mul_f32 v[112:113], v[112:113], v[116:117]
	v_pk_mul_f32 v[114:115], v[114:115], v[118:119]
	v_cvt_pk_bf16_f32 v120, v120, v121
	v_cvt_pk_bf16_f32 v121, v122, v123
	v_cvt_pk_bf16_f32 v122, v112, v113
	v_cvt_pk_bf16_f32 v123, v114, v115
	global_store_dwordx4 v[142:143], v[120:123], off
	v_lshl_add_u64 v[142:143], v[142:143], 0, s[98:99]
	v_pk_mul_f32 v[104:105], v[104:105], v[144:145] op_sel:[0,1]
	v_pk_mul_f32 v[106:107], v[106:107], v[144:145] op_sel:[0,1]
	v_pk_mul_f32 v[96:97], v[96:97], v[144:145] op_sel:[0,1]
	v_pk_mul_f32 v[98:99], v[98:99], v[144:145] op_sel:[0,1]
	v_pk_mul_f32 v[108:109], v[108:109], v[144:145] op_sel:[0,1]
	v_pk_mul_f32 v[110:111], v[110:111], v[144:145] op_sel:[0,1]
	v_pk_mul_f32 v[100:101], v[100:101], v[144:145] op_sel:[0,1]
	v_pk_mul_f32 v[102:103], v[102:103], v[144:145] op_sel:[0,1]
	v_pk_mul_f32 v[156:157], v[104:105], v[166:167]
	v_pk_mul_f32 v[158:159], v[106:107], v[166:167]
	v_pk_mul_f32 v[162:163], v[96:97], v[166:167]
	v_pk_mul_f32 v[164:165], v[98:99], v[166:167]
	v_exp_f32_e32 v156, v156
	v_exp_f32_e32 v157, v157
	v_exp_f32_e32 v158, v158
	v_exp_f32_e32 v159, v159
	v_exp_f32_e32 v162, v162
	v_exp_f32_e32 v163, v163
	v_exp_f32_e32 v164, v164
	v_exp_f32_e32 v165, v165
	v_add_f32_e32 v156, 1.0, v156
	v_add_f32_e32 v157, 1.0, v157
	v_add_f32_e32 v158, 1.0, v158
	v_add_f32_e32 v159, 1.0, v159
	v_add_f32_e32 v162, 1.0, v162
	v_add_f32_e32 v163, 1.0, v163
	v_add_f32_e32 v164, 1.0, v164
	v_add_f32_e32 v165, 1.0, v165
	v_rcp_f32_e32 v156, v156
	v_rcp_f32_e32 v157, v157
	v_rcp_f32_e32 v158, v158
	v_rcp_f32_e32 v159, v159
	v_rcp_f32_e32 v162, v162
	v_rcp_f32_e32 v163, v163
	v_rcp_f32_e32 v164, v164
	v_rcp_f32_e32 v165, v165
	v_pk_mul_f32 v[104:105], v[104:105], v[156:157]
	v_pk_mul_f32 v[106:107], v[106:107], v[158:159]
	v_pk_mul_f32 v[96:97], v[96:97], v[162:163]
	v_pk_mul_f32 v[98:99], v[98:99], v[164:165]
	v_pk_mul_f32 v[104:105], v[104:105], v[108:109]
	v_pk_mul_f32 v[106:107], v[106:107], v[110:111]
	v_pk_mul_f32 v[96:97], v[96:97], v[100:101]
	v_pk_mul_f32 v[98:99], v[98:99], v[102:103]
	v_cvt_pk_bf16_f32 v104, v104, v105
	v_cvt_pk_bf16_f32 v105, v106, v107
	v_cvt_pk_bf16_f32 v106, v96, v97
	v_cvt_pk_bf16_f32 v107, v98, v99
	global_store_dwordx4 v[142:143], v[104:107], off
	v_lshl_add_u64 v[142:143], v[142:143], 0, s[98:99]
	v_pk_mul_f32 v[88:89], v[88:89], v[146:147] op_sel_hi:[1,0]
	v_pk_mul_f32 v[90:91], v[90:91], v[146:147] op_sel_hi:[1,0]
	v_pk_mul_f32 v[80:81], v[80:81], v[146:147] op_sel_hi:[1,0]
	v_pk_mul_f32 v[82:83], v[82:83], v[146:147] op_sel_hi:[1,0]
	v_pk_mul_f32 v[92:93], v[92:93], v[146:147] op_sel_hi:[1,0]
	v_pk_mul_f32 v[94:95], v[94:95], v[146:147] op_sel_hi:[1,0]
	v_pk_mul_f32 v[84:85], v[84:85], v[146:147] op_sel_hi:[1,0]
	v_pk_mul_f32 v[86:87], v[86:87], v[146:147] op_sel_hi:[1,0]
	v_pk_mul_f32 v[156:157], v[88:89], v[166:167]
	v_pk_mul_f32 v[158:159], v[90:91], v[166:167]
	v_pk_mul_f32 v[162:163], v[80:81], v[166:167]
	v_pk_mul_f32 v[164:165], v[82:83], v[166:167]
	v_exp_f32_e32 v156, v156
	v_exp_f32_e32 v157, v157
	v_exp_f32_e32 v158, v158
	v_exp_f32_e32 v159, v159
	v_exp_f32_e32 v162, v162
	v_exp_f32_e32 v163, v163
	v_exp_f32_e32 v164, v164
	v_exp_f32_e32 v165, v165
	v_add_f32_e32 v156, 1.0, v156
	v_add_f32_e32 v157, 1.0, v157
	v_add_f32_e32 v158, 1.0, v158
	v_add_f32_e32 v159, 1.0, v159
	v_add_f32_e32 v162, 1.0, v162
	v_add_f32_e32 v163, 1.0, v163
	v_add_f32_e32 v164, 1.0, v164
	v_add_f32_e32 v165, 1.0, v165
	v_rcp_f32_e32 v156, v156
	v_rcp_f32_e32 v157, v157
	v_rcp_f32_e32 v158, v158
	v_rcp_f32_e32 v159, v159
	v_rcp_f32_e32 v162, v162
	v_rcp_f32_e32 v163, v163
	v_rcp_f32_e32 v164, v164
	v_rcp_f32_e32 v165, v165
	v_pk_mul_f32 v[88:89], v[88:89], v[156:157]
	v_pk_mul_f32 v[90:91], v[90:91], v[158:159]
	v_pk_mul_f32 v[80:81], v[80:81], v[162:163]
	v_pk_mul_f32 v[82:83], v[82:83], v[164:165]
	v_pk_mul_f32 v[88:89], v[88:89], v[92:93]
	v_pk_mul_f32 v[90:91], v[90:91], v[94:95]
	v_pk_mul_f32 v[80:81], v[80:81], v[84:85]
	v_pk_mul_f32 v[82:83], v[82:83], v[86:87]
	v_cvt_pk_bf16_f32 v88, v88, v89
	v_cvt_pk_bf16_f32 v89, v90, v91
	v_cvt_pk_bf16_f32 v90, v80, v81
	v_cvt_pk_bf16_f32 v91, v82, v83
	global_store_dwordx4 v[142:143], v[88:91], off
	v_lshl_add_u64 v[142:143], v[142:143], 0, s[98:99]
	v_pk_mul_f32 v[72:73], v[72:73], v[146:147] op_sel:[0,1]
	v_pk_mul_f32 v[74:75], v[74:75], v[146:147] op_sel:[0,1]
	v_pk_mul_f32 v[64:65], v[64:65], v[146:147] op_sel:[0,1]
	v_pk_mul_f32 v[66:67], v[66:67], v[146:147] op_sel:[0,1]
	v_pk_mul_f32 v[76:77], v[76:77], v[146:147] op_sel:[0,1]
	v_pk_mul_f32 v[78:79], v[78:79], v[146:147] op_sel:[0,1]
	v_pk_mul_f32 v[68:69], v[68:69], v[146:147] op_sel:[0,1]
	v_pk_mul_f32 v[70:71], v[70:71], v[146:147] op_sel:[0,1]
	v_pk_mul_f32 v[156:157], v[72:73], v[166:167]
	v_pk_mul_f32 v[158:159], v[74:75], v[166:167]
	v_pk_mul_f32 v[162:163], v[64:65], v[166:167]
	v_pk_mul_f32 v[164:165], v[66:67], v[166:167]
	v_exp_f32_e32 v156, v156
	v_exp_f32_e32 v157, v157
	v_exp_f32_e32 v158, v158
	v_exp_f32_e32 v159, v159
	v_exp_f32_e32 v162, v162
	v_exp_f32_e32 v163, v163
	v_exp_f32_e32 v164, v164
	v_exp_f32_e32 v165, v165
	v_add_f32_e32 v156, 1.0, v156
	v_add_f32_e32 v157, 1.0, v157
	v_add_f32_e32 v158, 1.0, v158
	v_add_f32_e32 v159, 1.0, v159
	v_add_f32_e32 v162, 1.0, v162
	v_add_f32_e32 v163, 1.0, v163
	v_add_f32_e32 v164, 1.0, v164
	v_add_f32_e32 v165, 1.0, v165
	v_rcp_f32_e32 v156, v156
	v_rcp_f32_e32 v157, v157
	v_rcp_f32_e32 v158, v158
	v_rcp_f32_e32 v159, v159
	v_rcp_f32_e32 v162, v162
	v_rcp_f32_e32 v163, v163
	v_rcp_f32_e32 v164, v164
	v_rcp_f32_e32 v165, v165
	v_pk_mul_f32 v[72:73], v[72:73], v[156:157]
; __device__ __forceinline__ unsigned cvt_pk_bf16(float lo, float hi) { unsigned r; asm volatile("v_cvt_pk_bf16_f32 %0, %1, %2" : "=v"(r) : "v"(lo), "v"(hi)); return r; }
; __device__ __forceinline__ float siluf_(float x) { return x * sigmoidf_(x); }
;     __device__ __forceinline__ void operator()(const f32x4 (&acc)[2][2][4][2], const Unit& u, int wr, int wc, int fr, int fq) const {
;     ...
;         for (int ai = 0; ai < 2; ++ai)
; #pragma unroll
;             for (int m = 0; m < 4; ++m) { const int row = row0 + ai * HALF + m * 16; bf16_t* rowp = O + (size_t)row * ldc + col0; const float rs = rsv[ai][m];
;                 f32x4 v0, v1;
; #pragma unroll
;                 for (int j = 0; j < 4; ++j) { v0[j] = siluf_(acc[ai][0][m][0][j] * rs) * (acc[ai][1][m][0][j] * rs); v1[j] = siluf_(acc[ai][0][m][1][j] * rs) * (acc[ai][1][m][1][j] * rs); }
;                 u32x4 w; w.x = cvt_pk_bf16(v0[0], v0[1]); w.y = cvt_pk_bf16(v0[2], v0[3]); w.z = cvt_pk_bf16(v1[0], v1[1]); w.w = cvt_pk_bf16(v1[2], v1[3]);
;                 *(u32x4*)rowp = w; }
	v_pk_mul_f32 v[74:75], v[74:75], v[158:159]
	v_pk_mul_f32 v[64:65], v[64:65], v[162:163]
	v_pk_mul_f32 v[66:67], v[66:67], v[164:165]
	v_pk_mul_f32 v[72:73], v[72:73], v[76:77]
	v_pk_mul_f32 v[74:75], v[74:75], v[78:79]
	v_pk_mul_f32 v[64:65], v[64:65], v[68:69]
	v_pk_mul_f32 v[66:67], v[66:67], v[70:71]
	v_cvt_pk_bf16_f32 v72, v72, v73
	v_cvt_pk_bf16_f32 v73, v74, v75
	v_cvt_pk_bf16_f32 v74, v64, v65
	v_cvt_pk_bf16_f32 v75, v66, v67
	global_store_dwordx4 v[142:143], v[72:75], off
	v_lshl_add_u64 v[142:143], v[142:143], 0, s[100:101]
	v_pk_mul_f32 v[56:57], v[56:57], v[148:149] op_sel_hi:[1,0]
	v_pk_mul_f32 v[58:59], v[58:59], v[148:149] op_sel_hi:[1,0]
	v_pk_mul_f32 v[48:49], v[48:49], v[148:149] op_sel_hi:[1,0]
	v_pk_mul_f32 v[50:51], v[50:51], v[148:149] op_sel_hi:[1,0]
	v_pk_mul_f32 v[60:61], v[60:61], v[148:149] op_sel_hi:[1,0]
	v_pk_mul_f32 v[62:63], v[62:63], v[148:149] op_sel_hi:[1,0]
	v_pk_mul_f32 v[52:53], v[52:53], v[148:149] op_sel_hi:[1,0]
	v_pk_mul_f32 v[54:55], v[54:55], v[148:149] op_sel_hi:[1,0]
	v_pk_mul_f32 v[156:157], v[56:57], v[166:167]
	v_pk_mul_f32 v[158:159], v[58:59], v[166:167]
	v_pk_mul_f32 v[162:163], v[48:49], v[166:167]
	v_pk_mul_f32 v[164:165], v[50:51], v[166:167]
	v_exp_f32_e32 v156, v156
	v_exp_f32_e32 v157, v157
	v_exp_f32_e32 v158, v158
	v_exp_f32_e32 v159, v159
	v_exp_f32_e32 v162, v162
	v_exp_f32_e32 v163, v163
	v_exp_f32_e32 v164, v164
	v_exp_f32_e32 v165, v165
	v_add_f32_e32 v156, 1.0, v156
	v_add_f32_e32 v157, 1.0, v157
	v_add_f32_e32 v158, 1.0, v158
	v_add_f32_e32 v159, 1.0, v159
	v_add_f32_e32 v162, 1.0, v162
	v_add_f32_e32 v163, 1.0, v163
	v_add_f32_e32 v164, 1.0, v164
	v_add_f32_e32 v165, 1.0, v165
	v_rcp_f32_e32 v156, v156
	v_rcp_f32_e32 v157, v157
	v_rcp_f32_e32 v158, v158
	v_rcp_f32_e32 v159, v159
	v_rcp_f32_e32 v162, v162
	v_rcp_f32_e32 v163, v163
	v_rcp_f32_e32 v164, v164
	v_rcp_f32_e32 v165, v165
	v_pk_mul_f32 v[56:57], v[56:57], v[156:157]
	v_pk_mul_f32 v[58:59], v[58:59], v[158:159]
	v_pk_mul_f32 v[48:49], v[48:49], v[162:163]
	v_pk_mul_f32 v[50:51], v[50:51], v[164:165]
	v_pk_mul_f32 v[56:57], v[56:57], v[60:61]
	v_pk_mul_f32 v[58:59], v[58:59], v[62:63]
	v_pk_mul_f32 v[48:49], v[48:49], v[52:53]
	v_pk_mul_f32 v[50:51], v[50:51], v[54:55]
	v_cvt_pk_bf16_f32 v56, v56, v57
	v_cvt_pk_bf16_f32 v57, v58, v59
	v_cvt_pk_bf16_f32 v58, v48, v49
	v_cvt_pk_bf16_f32 v59, v50, v51
	global_store_dwordx4 v[142:143], v[56:59], off
	v_lshl_add_u64 v[142:143], v[142:143], 0, s[98:99]
	v_pk_mul_f32 v[40:41], v[40:41], v[148:149] op_sel:[0,1]
	v_pk_mul_f32 v[42:43], v[42:43], v[148:149] op_sel:[0,1]
	v_pk_mul_f32 v[32:33], v[32:33], v[148:149] op_sel:[0,1]
	v_pk_mul_f32 v[34:35], v[34:35], v[148:149] op_sel:[0,1]
	v_pk_mul_f32 v[44:45], v[44:45], v[148:149] op_sel:[0,1]
	v_pk_mul_f32 v[46:47], v[46:47], v[148:149] op_sel:[0,1]
	v_pk_mul_f32 v[36:37], v[36:37], v[148:149] op_sel:[0,1]
	v_pk_mul_f32 v[38:39], v[38:39], v[148:149] op_sel:[0,1]
	v_pk_mul_f32 v[156:157], v[40:41], v[166:167]
	v_pk_mul_f32 v[158:159], v[42:43], v[166:167]
	v_pk_mul_f32 v[162:163], v[32:33], v[166:167]
	v_pk_mul_f32 v[164:165], v[34:35], v[166:167]
	v_exp_f32_e32 v156, v156
	v_exp_f32_e32 v157, v157
	v_exp_f32_e32 v158, v158
	v_exp_f32_e32 v159, v159
	v_exp_f32_e32 v162, v162
	v_exp_f32_e32 v163, v163
	v_exp_f32_e32 v164, v164
	v_exp_f32_e32 v165, v165
	v_add_f32_e32 v156, 1.0, v156
	v_add_f32_e32 v157, 1.0, v157
	v_add_f32_e32 v158, 1.0, v158
	v_add_f32_e32 v159, 1.0, v159
	v_add_f32_e32 v162, 1.0, v162
	v_add_f32_e32 v163, 1.0, v163
	v_add_f32_e32 v164, 1.0, v164
	v_add_f32_e32 v165, 1.0, v165
	v_rcp_f32_e32 v156, v156
	v_rcp_f32_e32 v157, v157
	v_rcp_f32_e32 v158, v158
	v_rcp_f32_e32 v159, v159
	v_rcp_f32_e32 v162, v162
	v_rcp_f32_e32 v163, v163
	v_rcp_f32_e32 v164, v164
	v_rcp_f32_e32 v165, v165
	v_pk_mul_f32 v[40:41], v[40:41], v[156:157]
	v_pk_mul_f32 v[42:43], v[42:43], v[158:159]
	v_pk_mul_f32 v[32:33], v[32:33], v[162:163]
	v_pk_mul_f32 v[34:35], v[34:35], v[164:165]
	v_pk_mul_f32 v[40:41], v[40:41], v[44:45]
	v_pk_mul_f32 v[42:43], v[42:43], v[46:47]
	v_pk_mul_f32 v[32:33], v[32:33], v[36:37]
	v_pk_mul_f32 v[34:35], v[34:35], v[38:39]
; __device__ __forceinline__ unsigned cvt_pk_bf16(float lo, float hi) { unsigned r; asm volatile("v_cvt_pk_bf16_f32 %0, %1, %2" : "=v"(r) : "v"(lo), "v"(hi)); return r; }
; __device__ __forceinline__ float siluf_(float x) { return x * sigmoidf_(x); }
; #define PG8_BAR __builtin_amdgcn_s_barrier()
;     __device__ __forceinline__ void operator()(const f32x4 (&acc)[2][2][4][2], const Unit& u, int wr, int wc, int fr, int fq) const {
;     ...
;         for (int ai = 0; ai < 2; ++ai)
; #pragma unroll
;             for (int m = 0; m < 4; ++m) { const int row = row0 + ai * HALF + m * 16; bf16_t* rowp = O + (size_t)row * ldc + col0; const float rs = rsv[ai][m];
;                 f32x4 v0, v1;
; #pragma unroll
;                 for (int j = 0; j < 4; ++j) { v0[j] = siluf_(acc[ai][0][m][0][j] * rs) * (acc[ai][1][m][0][j] * rs); v1[j] = siluf_(acc[ai][0][m][1][j] * rs) * (acc[ai][1][m][1][j] * rs); }
;                 u32x4 w; w.x = cvt_pk_bf16(v0[0], v0[1]); w.y = cvt_pk_bf16(v0[2], v0[3]); w.z = cvt_pk_bf16(v1[0], v1[1]); w.w = cvt_pk_bf16(v1[2], v1[3]);
;                 *(u32x4*)rowp = w; }
; template <class Epi, bool ALIGN_EPI>
; __device__ __forceinline__ void gemm_phase(LAS unsigned char* lds, const Gemm g, const StaticOrder& S, const Epi& E, const int tid) {
;     ...
;         if (!has_next) break;
; #pragma unroll
;         for (int a = 0; a < 2; ++a)
; #pragma unroll
;             for (int b = 0; b < 2; ++b)
; #pragma unroll
;                 for (int m = 0; m < 4; ++m)
; #pragma unroll
;                     for (int n = 0; n < 2; ++n) acc[a][b][m][n] = (f32x4){0.f, 0.f, 0.f, 0.f};
;         cur = nxt; cA = nA; cB = nB; ++ui;
;         if constexpr (ALIGN_EPI) { if (wr == 1) PG8_BAR; }
	v_cvt_pk_bf16_f32 v40, v40, v41
	v_cvt_pk_bf16_f32 v41, v42, v43
	v_cvt_pk_bf16_f32 v42, v32, v33
	v_cvt_pk_bf16_f32 v43, v34, v35
	global_store_dwordx4 v[142:143], v[40:43], off
	v_lshl_add_u64 v[142:143], v[142:143], 0, s[98:99]
	v_pk_mul_f32 v[24:25], v[24:25], v[154:155] op_sel_hi:[1,0]
	v_pk_mul_f32 v[26:27], v[26:27], v[154:155] op_sel_hi:[1,0]
	v_pk_mul_f32 v[16:17], v[16:17], v[154:155] op_sel_hi:[1,0]
	v_pk_mul_f32 v[18:19], v[18:19], v[154:155] op_sel_hi:[1,0]
	v_pk_mul_f32 v[28:29], v[28:29], v[154:155] op_sel_hi:[1,0]
	v_pk_mul_f32 v[30:31], v[30:31], v[154:155] op_sel_hi:[1,0]
	v_pk_mul_f32 v[20:21], v[20:21], v[154:155] op_sel_hi:[1,0]
	v_pk_mul_f32 v[22:23], v[22:23], v[154:155] op_sel_hi:[1,0]
	v_pk_mul_f32 v[156:157], v[24:25], v[166:167]
	v_pk_mul_f32 v[158:159], v[26:27], v[166:167]
	v_pk_mul_f32 v[162:163], v[16:17], v[166:167]
	v_pk_mul_f32 v[164:165], v[18:19], v[166:167]
	v_exp_f32_e32 v156, v156
	v_exp_f32_e32 v157, v157
	v_exp_f32_e32 v158, v158
	v_exp_f32_e32 v159, v159
	v_exp_f32_e32 v162, v162
	v_exp_f32_e32 v163, v163
	v_exp_f32_e32 v164, v164
	v_exp_f32_e32 v165, v165
	v_add_f32_e32 v156, 1.0, v156
	v_add_f32_e32 v157, 1.0, v157
	v_add_f32_e32 v158, 1.0, v158
	v_add_f32_e32 v159, 1.0, v159
	v_add_f32_e32 v162, 1.0, v162
	v_add_f32_e32 v163, 1.0, v163
	v_add_f32_e32 v164, 1.0, v164
	v_add_f32_e32 v165, 1.0, v165
	v_rcp_f32_e32 v156, v156
	v_rcp_f32_e32 v157, v157
	v_rcp_f32_e32 v158, v158
	v_rcp_f32_e32 v159, v159
	v_rcp_f32_e32 v162, v162
	v_rcp_f32_e32 v163, v163
	v_rcp_f32_e32 v164, v164
	v_rcp_f32_e32 v165, v165
	v_pk_mul_f32 v[24:25], v[24:25], v[156:157]
	v_pk_mul_f32 v[26:27], v[26:27], v[158:159]
	v_pk_mul_f32 v[16:17], v[16:17], v[162:163]
	v_pk_mul_f32 v[18:19], v[18:19], v[164:165]
	v_pk_mul_f32 v[24:25], v[24:25], v[28:29]
	v_pk_mul_f32 v[26:27], v[26:27], v[30:31]
	v_pk_mul_f32 v[16:17], v[16:17], v[20:21]
	v_pk_mul_f32 v[18:19], v[18:19], v[22:23]
	v_cvt_pk_bf16_f32 v24, v24, v25
	v_cvt_pk_bf16_f32 v25, v26, v27
	v_cvt_pk_bf16_f32 v26, v16, v17
	v_cvt_pk_bf16_f32 v27, v18, v19
	global_store_dwordx4 v[142:143], v[24:27], off
	v_lshl_add_u64 v[142:143], v[142:143], 0, s[98:99]
	v_pk_mul_f32 v[8:9], v[8:9], v[154:155] op_sel:[0,1]
	v_pk_mul_f32 v[10:11], v[10:11], v[154:155] op_sel:[0,1]
	v_pk_mul_f32 v[4:5], v[4:5], v[154:155] op_sel:[0,1]
	v_pk_mul_f32 v[6:7], v[6:7], v[154:155] op_sel:[0,1]
	v_pk_mul_f32 v[12:13], v[12:13], v[154:155] op_sel:[0,1]
	v_pk_mul_f32 v[14:15], v[14:15], v[154:155] op_sel:[0,1]
	v_pk_mul_f32 v[0:1], v[0:1], v[154:155] op_sel:[0,1]
	v_pk_mul_f32 v[2:3], v[2:3], v[154:155] op_sel:[0,1]
	v_pk_mul_f32 v[156:157], v[8:9], v[166:167]
	v_pk_mul_f32 v[158:159], v[10:11], v[166:167]
	v_pk_mul_f32 v[162:163], v[4:5], v[166:167]
	v_pk_mul_f32 v[164:165], v[6:7], v[166:167]
	v_exp_f32_e32 v156, v156
	v_exp_f32_e32 v157, v157
	v_exp_f32_e32 v158, v158
	v_exp_f32_e32 v159, v159
	v_exp_f32_e32 v162, v162
	v_exp_f32_e32 v163, v163
	v_exp_f32_e32 v164, v164
	v_exp_f32_e32 v165, v165
	v_add_f32_e32 v156, 1.0, v156
	v_add_f32_e32 v157, 1.0, v157
	v_add_f32_e32 v158, 1.0, v158
	v_add_f32_e32 v159, 1.0, v159
	v_add_f32_e32 v162, 1.0, v162
	v_add_f32_e32 v163, 1.0, v163
	v_add_f32_e32 v164, 1.0, v164
	v_add_f32_e32 v165, 1.0, v165
	v_rcp_f32_e32 v156, v156
	v_rcp_f32_e32 v157, v157
	v_rcp_f32_e32 v158, v158
	v_rcp_f32_e32 v159, v159
	v_rcp_f32_e32 v162, v162
	v_rcp_f32_e32 v163, v163
	v_rcp_f32_e32 v164, v164
	v_rcp_f32_e32 v165, v165
	v_pk_mul_f32 v[8:9], v[8:9], v[156:157]
	v_pk_mul_f32 v[10:11], v[10:11], v[158:159]
	v_pk_mul_f32 v[4:5], v[4:5], v[162:163]
	v_pk_mul_f32 v[6:7], v[6:7], v[164:165]
	v_pk_mul_f32 v[8:9], v[8:9], v[12:13]
	v_pk_mul_f32 v[10:11], v[10:11], v[14:15]
	v_pk_mul_f32 v[4:5], v[4:5], v[0:1]
	v_pk_mul_f32 v[6:7], v[6:7], v[2:3]
	v_cvt_pk_bf16_f32 v8, v8, v9
	v_cvt_pk_bf16_f32 v9, v10, v11
	v_cvt_pk_bf16_f32 v10, v4, v5
	v_cvt_pk_bf16_f32 v11, v6, v7
	global_store_dwordx4 v[142:143], v[8:11], off
	s_mov_b64 s[10:11], -1
	s_and_b64 vcc, exec, s[8:9]
	s_cbranch_vccnz .LBB0_299
	s_andn2_b64 vcc, exec, s[40:41]
	s_cbranch_vccnz .LBB0_298
	s_barrier
	s_branch .LBB0_298

; __global__ void __launch_bounds__(512, 2) fwd_kernel(Args args) {
	.amdhsa_kernel _Z10fwd_kernel4Args
		.amdhsa_group_segment_fixed_size 0
		.amdhsa_private_segment_fixed_size 0
		.amdhsa_kernarg_size 464
		.amdhsa_user_sgpr_count 2
		.amdhsa_user_sgpr_dispatch_ptr 0
		.amdhsa_user_sgpr_queue_ptr 0
		.amdhsa_user_sgpr_kernarg_segment_ptr 1
		.amdhsa_user_sgpr_dispatch_id 0
		.amdhsa_user_sgpr_kernarg_preload_length 0
		.amdhsa_user_sgpr_kernarg_preload_offset 0
		.amdhsa_user_sgpr_private_segment_size 0
		.amdhsa_uses_dynamic_stack 0
		.amdhsa_enable_private_segment 0
		.amdhsa_system_sgpr_workgroup_id_x 1
		.amdhsa_system_sgpr_workgroup_id_y 0
		.amdhsa_system_sgpr_workgroup_id_z 0
		.amdhsa_system_sgpr_workgroup_info 0
		.amdhsa_system_vgpr_workitem_id 2
		.amdhsa_next_free_vgpr 256
		.amdhsa_next_free_sgpr 102
		.amdhsa_accum_offset 256
		.amdhsa_reserve_vcc 1
		.amdhsa_float_round_mode_32 0
		.amdhsa_float_round_mode_16_64 0
		.amdhsa_float_denorm_mode_32 3
		.amdhsa_float_denorm_mode_16_64 3
		.amdhsa_dx10_clamp 1
		.amdhsa_ieee_mode 1
		.amdhsa_fp16_overflow 0
		.amdhsa_tg_split 0
		.amdhsa_exception_fp_ieee_invalid_op 0
		.amdhsa_exception_fp_denorm_src 0
		.amdhsa_exception_fp_ieee_div_zero 0
		.amdhsa_exception_fp_ieee_overflow 0
		.amdhsa_exception_fp_ieee_underflow 0
		.amdhsa_exception_fp_ieee_inexact 0
		.amdhsa_exception_int_div_zero 0
	.end_amdhsa_kernel
